# skip L2 writeback in group barrier when all group WGs on one XCD
# speedup vs baseline: 1.0134x; 1.0134x over previous
; __device__ __forceinline__ unsigned xb_ld(unsigned* p)              { return __hip_atomic_load(p, __ATOMIC_RELAXED, __HIP_MEMORY_SCOPE_AGENT); }
; __device__ __forceinline__ unsigned xb_add(unsigned* p, unsigned v) { return __hip_atomic_fetch_add(p, v, __ATOMIC_RELAXED, __HIP_MEMORY_SCOPE_AGENT); }
; #define XB_SPIN(cond, bar) do { unsigned _sp = 0; while (cond) { __builtin_amdgcn_s_sleep(1); \
;     if ((++_sp & 255u) == 0u) { if (xb_ld(&(bar)[XB_TMO])) break; if (_sp > XB_SPIN_CAP) { atomicAdd(&(bar)[XB_TMO], 1u); break; } } } } while (0)
; __device__ __forceinline__ void xcd_barrier(const XcdBarrier& b) {
;     ...
;         const unsigned old = xb_add(&bar[XB_XSUB(b.x)], 1u);
;         const unsigned gen = old / nloc;
;         if (old + 1u == (gen + 1u) * nloc) {
;             __builtin_amdgcn_fence(__ATOMIC_RELEASE, "agent");
;             asm volatile("s_waitcnt vmcnt(0)" ::: "memory");
;             const unsigned og = xb_add(&bar[XB_TOP], 1u);
;             const unsigned tg = og / nx;
;             if (og + 1u == (tg + 1u) * nx) xb_add(&bar[XB_TOPGEN], 1u);
;             else XB_SPIN(xb_ld(&bar[XB_TOPGEN]) == tg, bar);
;             __builtin_amdgcn_fence(__ATOMIC_ACQUIRE, "agent");
;             xb_add(&bar[XB_XGEN(b.x)], 1u);
;             asm volatile("s_waitcnt vmcnt(0)" ::: "memory");
.LBB0_212:
	s_andn2_saveexec_b64 s[20:21], s[36:37]
	s_cbranch_execz .LBB0_228
	s_waitcnt lgkmcnt(0)
	v_cmp_eq_u32_e32 vcc, 1, v0
	s_cbranch_vccnz .Lwbskip_1
	buffer_wbl2 sc1
.Lwbskip_1:
	s_waitcnt vmcnt(0)
	v_mov_b32_e32 v1, 0x3000
	v_mov_b32_e32 v2, 1
	global_atomic_add v1, v1, v2, s[54:55] offset:1024 sc0
	v_cvt_f32_u32_e32 v2, v0
	v_sub_u32_e32 v3, 0, v0
	s_add_u32 s36, s54, 0x3500
	s_addc_u32 s37, s55, 0
	v_rcp_iflag_f32_e32 v2, v2
	s_mov_b64 s[40:41], -1
	v_mul_f32_e32 v2, 0x4f7ffffe, v2
	v_cvt_u32_f32_e32 v2, v2
	v_mul_lo_u32 v3, v3, v2
	v_mul_hi_u32 v3, v2, v3
	v_add_u32_e32 v2, v2, v3
	s_waitcnt vmcnt(0)
	v_mul_hi_u32 v2, v1, v2
	v_mul_lo_u32 v4, v2, v0
	v_add_u32_e32 v3, 1, v1
	v_sub_u32_e32 v1, v1, v4
	v_add_u32_e32 v5, 1, v2
	v_cmp_ge_u32_e32 vcc, v1, v0
	v_sub_u32_e32 v4, v1, v0
	s_nop 0
	v_cndmask_b32_e32 v2, v2, v5, vcc
	v_cndmask_b32_e32 v1, v1, v4, vcc
	v_add_u32_e32 v4, 1, v2
	v_cmp_ge_u32_e32 vcc, v1, v0
	s_nop 1
	v_cndmask_b32_e32 v2, v2, v4, vcc
	v_mul_lo_u32 v1, v0, v2
	v_add_u32_e32 v0, v1, v0
	v_cmp_ne_u32_e32 vcc, v3, v0
	v_mov_b64_e32 v[0:1], s[36:37]
	s_and_saveexec_b64 s[38:39], vcc
	s_cbranch_execz .LBB0_225
	v_mov_b32_e32 v0, 0
	global_load_dword v1, v0, s[36:37] sc1
	s_mov_b64 s[46:47], 0
	s_waitcnt vmcnt(0)
	v_cmp_eq_u32_e32 vcc, v1, v2
	s_and_saveexec_b64 s[44:45], vcc
	s_cbranch_execz .LBB0_224
	s_add_u32 s40, s54, 0x200
	s_addc_u32 s41, s55, 0
	s_mov_b32 s11, 1
	s_branch .LBB0_217

; __device__ __forceinline__ unsigned xb_ld(unsigned* p)              { return __hip_atomic_load(p, __ATOMIC_RELAXED, __HIP_MEMORY_SCOPE_AGENT); }
; __device__ __forceinline__ unsigned xb_add(unsigned* p, unsigned v) { return __hip_atomic_fetch_add(p, v, __ATOMIC_RELAXED, __HIP_MEMORY_SCOPE_AGENT); }
; #define XB_SPIN(cond, bar) do { unsigned _sp = 0; while (cond) { __builtin_amdgcn_s_sleep(1); \
;     if ((++_sp & 255u) == 0u) { if (xb_ld(&(bar)[XB_TMO])) break; if (_sp > XB_SPIN_CAP) { atomicAdd(&(bar)[XB_TMO], 1u); break; } } } } while (0)
; __device__ __forceinline__ void xcd_barrier(const XcdBarrier& b) {
;     ...
;         const unsigned old = xb_add(&bar[XB_XSUB(b.x)], 1u);
;         const unsigned gen = old / nloc;
;         if (old + 1u == (gen + 1u) * nloc) {
;             __builtin_amdgcn_fence(__ATOMIC_RELEASE, "agent");
;             asm volatile("s_waitcnt vmcnt(0)" ::: "memory");
;             const unsigned og = xb_add(&bar[XB_TOP], 1u);
;             const unsigned tg = og / nx;
;             if (og + 1u == (tg + 1u) * nx) xb_add(&bar[XB_TOPGEN], 1u);
;             else XB_SPIN(xb_ld(&bar[XB_TOPGEN]) == tg, bar);
;             __builtin_amdgcn_fence(__ATOMIC_ACQUIRE, "agent");
;             xb_add(&bar[XB_XGEN(b.x)], 1u);
;             asm volatile("s_waitcnt vmcnt(0)" ::: "memory");
.LBB0_397:
	s_andn2_saveexec_b64 s[20:21], s[44:45]
	s_cbranch_execz .LBB0_413
	s_waitcnt lgkmcnt(0)
	v_cmp_eq_u32_e32 vcc, 1, v0
	s_cbranch_vccnz .Lwbskip_3
	buffer_wbl2 sc1
.Lwbskip_3:
	s_waitcnt vmcnt(0)
	v_mov_b32_e32 v1, 0x3000
	v_mov_b32_e32 v2, 1
	global_atomic_add v1, v1, v2, s[54:55] offset:1024 sc0
	v_cvt_f32_u32_e32 v2, v0
	v_sub_u32_e32 v3, 0, v0
	s_add_u32 s44, s54, 0x3500
	s_addc_u32 s45, s55, 0
	v_rcp_iflag_f32_e32 v2, v2
	s_mov_b64 s[56:57], -1
	v_mul_f32_e32 v2, 0x4f7ffffe, v2
	v_cvt_u32_f32_e32 v2, v2
	v_mul_lo_u32 v3, v3, v2
	v_mul_hi_u32 v3, v2, v3
	v_add_u32_e32 v2, v2, v3
	s_waitcnt vmcnt(0)
	v_mul_hi_u32 v2, v1, v2
	v_mul_lo_u32 v4, v2, v0
	v_add_u32_e32 v3, 1, v1
	v_sub_u32_e32 v1, v1, v4
	v_add_u32_e32 v5, 1, v2
	v_cmp_ge_u32_e32 vcc, v1, v0
	v_sub_u32_e32 v4, v1, v0
	s_nop 0
	v_cndmask_b32_e32 v2, v2, v5, vcc
	v_cndmask_b32_e32 v1, v1, v4, vcc
	v_add_u32_e32 v4, 1, v2
	v_cmp_ge_u32_e32 vcc, v1, v0
	s_nop 1
	v_cndmask_b32_e32 v2, v2, v4, vcc
	v_mul_lo_u32 v1, v0, v2
	v_add_u32_e32 v0, v1, v0
	v_cmp_ne_u32_e32 vcc, v3, v0
	v_mov_b64_e32 v[0:1], s[44:45]
	s_and_saveexec_b64 s[50:51], vcc
	s_cbranch_execz .LBB0_410
	v_mov_b32_e32 v0, 0
	global_load_dword v1, v0, s[44:45] sc1
	s_mov_b64 s[60:61], 0
	s_waitcnt vmcnt(0)
	v_cmp_eq_u32_e32 vcc, v1, v2
	s_and_saveexec_b64 s[58:59], vcc
	s_cbranch_execz .LBB0_409
	s_add_u32 s56, s54, 0x200
	s_addc_u32 s57, s55, 0
	s_mov_b32 s11, 1
	s_branch .LBB0_402

; __device__ __forceinline__ unsigned xb_ld(unsigned* p)              { return __hip_atomic_load(p, __ATOMIC_RELAXED, __HIP_MEMORY_SCOPE_AGENT); }
; __device__ __forceinline__ unsigned xb_add(unsigned* p, unsigned v) { return __hip_atomic_fetch_add(p, v, __ATOMIC_RELAXED, __HIP_MEMORY_SCOPE_AGENT); }
; #define XB_SPIN(cond, bar) do { unsigned _sp = 0; while (cond) { __builtin_amdgcn_s_sleep(1); \
;     if ((++_sp & 255u) == 0u) { if (xb_ld(&(bar)[XB_TMO])) break; if (_sp > XB_SPIN_CAP) { atomicAdd(&(bar)[XB_TMO], 1u); break; } } } } while (0)
; __device__ __forceinline__ void xcd_barrier(const XcdBarrier& b) {
;     ...
;         const unsigned old = xb_add(&bar[XB_XSUB(b.x)], 1u);
;         const unsigned gen = old / nloc;
;         if (old + 1u == (gen + 1u) * nloc) {
;             __builtin_amdgcn_fence(__ATOMIC_RELEASE, "agent");
;             asm volatile("s_waitcnt vmcnt(0)" ::: "memory");
;             const unsigned og = xb_add(&bar[XB_TOP], 1u);
;             const unsigned tg = og / nx;
;             if (og + 1u == (tg + 1u) * nx) xb_add(&bar[XB_TOPGEN], 1u);
;             else XB_SPIN(xb_ld(&bar[XB_TOPGEN]) == tg, bar);
;             __builtin_amdgcn_fence(__ATOMIC_ACQUIRE, "agent");
;             xb_add(&bar[XB_XGEN(b.x)], 1u);
;             asm volatile("s_waitcnt vmcnt(0)" ::: "memory");
.LBB0_452:
	s_andn2_saveexec_b64 s[20:21], s[60:61]
	s_cbranch_execz .LBB0_468
	s_waitcnt lgkmcnt(0)
	v_cmp_eq_u32_e32 vcc, 1, v0
	s_cbranch_vccnz .Lwbskip_4
	buffer_wbl2 sc1
.Lwbskip_4:
	s_waitcnt vmcnt(0)
	v_mov_b32_e32 v1, 0x3000
	v_mov_b32_e32 v2, 1
	global_atomic_add v1, v1, v2, s[54:55] offset:1024 sc0
	v_cvt_f32_u32_e32 v2, v0
	v_sub_u32_e32 v3, 0, v0
	s_add_u32 s60, s54, 0x3500
	s_addc_u32 s61, s55, 0
	v_rcp_iflag_f32_e32 v2, v2
	s_mov_b64 s[64:65], -1
	v_mul_f32_e32 v2, 0x4f7ffffe, v2
	v_cvt_u32_f32_e32 v2, v2
	v_mul_lo_u32 v3, v3, v2
	v_mul_hi_u32 v3, v2, v3
	v_add_u32_e32 v2, v2, v3
	s_waitcnt vmcnt(0)
	v_mul_hi_u32 v2, v1, v2
	v_mul_lo_u32 v4, v2, v0
	v_add_u32_e32 v3, 1, v1
	v_sub_u32_e32 v1, v1, v4
	v_add_u32_e32 v5, 1, v2
	v_cmp_ge_u32_e32 vcc, v1, v0
	v_sub_u32_e32 v4, v1, v0
	s_nop 0
	v_cndmask_b32_e32 v2, v2, v5, vcc
	v_cndmask_b32_e32 v1, v1, v4, vcc
	v_add_u32_e32 v4, 1, v2
	v_cmp_ge_u32_e32 vcc, v1, v0
	s_nop 1
	v_cndmask_b32_e32 v2, v2, v4, vcc
	v_mul_lo_u32 v1, v0, v2
	v_add_u32_e32 v0, v1, v0
	v_cmp_ne_u32_e32 vcc, v3, v0
	v_mov_b64_e32 v[0:1], s[60:61]
	s_and_saveexec_b64 s[62:63], vcc
	s_cbranch_execz .LBB0_465
	v_mov_b32_e32 v0, 0
	global_load_dword v1, v0, s[60:61] sc1
	s_mov_b64 s[68:69], 0
	s_waitcnt vmcnt(0)
	v_cmp_eq_u32_e32 vcc, v1, v2
	s_and_saveexec_b64 s[66:67], vcc
	s_cbranch_execz .LBB0_464
	s_add_u32 s64, s54, 0x200
	s_addc_u32 s65, s55, 0
	s_mov_b32 s11, 1
	s_branch .LBB0_457

; __device__ __forceinline__ unsigned xb_ld(unsigned* p)              { return __hip_atomic_load(p, __ATOMIC_RELAXED, __HIP_MEMORY_SCOPE_AGENT); }
; __device__ __forceinline__ unsigned xb_add(unsigned* p, unsigned v) { return __hip_atomic_fetch_add(p, v, __ATOMIC_RELAXED, __HIP_MEMORY_SCOPE_AGENT); }
; #define XB_SPIN(cond, bar) do { unsigned _sp = 0; while (cond) { __builtin_amdgcn_s_sleep(1); \
;     if ((++_sp & 255u) == 0u) { if (xb_ld(&(bar)[XB_TMO])) break; if (_sp > XB_SPIN_CAP) { atomicAdd(&(bar)[XB_TMO], 1u); break; } } } } while (0)
; __device__ __forceinline__ void xcd_barrier(const XcdBarrier& b) {
;     ...
;         const unsigned old = xb_add(&bar[XB_XSUB(b.x)], 1u);
;         const unsigned gen = old / nloc;
;         if (old + 1u == (gen + 1u) * nloc) {
;             __builtin_amdgcn_fence(__ATOMIC_RELEASE, "agent");
;             asm volatile("s_waitcnt vmcnt(0)" ::: "memory");
;             const unsigned og = xb_add(&bar[XB_TOP], 1u);
;             const unsigned tg = og / nx;
;             if (og + 1u == (tg + 1u) * nx) xb_add(&bar[XB_TOPGEN], 1u);
;             else XB_SPIN(xb_ld(&bar[XB_TOPGEN]) == tg, bar);
;             __builtin_amdgcn_fence(__ATOMIC_ACQUIRE, "agent");
;             xb_add(&bar[XB_XGEN(b.x)], 1u);
;             asm volatile("s_waitcnt vmcnt(0)" ::: "memory");
.LBB0_503:
	s_andn2_saveexec_b64 s[2:3], s[62:63]
	s_cbranch_execz .LBB0_519
	s_waitcnt lgkmcnt(0)
	v_cmp_eq_u32_e32 vcc, 1, v0
	s_cbranch_vccnz .Lwbskip_5
	buffer_wbl2 sc1
.Lwbskip_5:
	s_waitcnt vmcnt(0)
	v_mov_b32_e32 v1, 0x3000
	v_mov_b32_e32 v2, 1
	global_atomic_add v1, v1, v2, s[54:55] offset:1024 sc0
	v_cvt_f32_u32_e32 v2, v0
	v_sub_u32_e32 v3, 0, v0
	s_add_u32 s62, s54, 0x3500
	s_addc_u32 s63, s55, 0
	v_rcp_iflag_f32_e32 v2, v2
	s_mov_b64 s[66:67], -1
	v_mul_f32_e32 v2, 0x4f7ffffe, v2
	v_cvt_u32_f32_e32 v2, v2
	v_mul_lo_u32 v3, v3, v2
	v_mul_hi_u32 v3, v2, v3
	v_add_u32_e32 v2, v2, v3
	s_waitcnt vmcnt(0)
	v_mul_hi_u32 v2, v1, v2
	v_mul_lo_u32 v4, v2, v0
	v_add_u32_e32 v3, 1, v1
	v_sub_u32_e32 v1, v1, v4
	v_add_u32_e32 v5, 1, v2
	v_cmp_ge_u32_e32 vcc, v1, v0
	v_sub_u32_e32 v4, v1, v0
	s_nop 0
	v_cndmask_b32_e32 v2, v2, v5, vcc
	v_cndmask_b32_e32 v1, v1, v4, vcc
	v_add_u32_e32 v4, 1, v2
	v_cmp_ge_u32_e32 vcc, v1, v0
	s_nop 1
	v_cndmask_b32_e32 v2, v2, v4, vcc
	v_mul_lo_u32 v1, v0, v2
	v_add_u32_e32 v0, v1, v0
	v_cmp_ne_u32_e32 vcc, v3, v0
	v_mov_b64_e32 v[0:1], s[62:63]
	s_and_saveexec_b64 s[64:65], vcc
	s_cbranch_execz .LBB0_516
	v_mov_b32_e32 v0, 0
	global_load_dword v1, v0, s[62:63] sc1
	s_mov_b64 s[70:71], 0
	s_waitcnt vmcnt(0)
	v_cmp_eq_u32_e32 vcc, v1, v2
	s_and_saveexec_b64 s[68:69], vcc
	s_cbranch_execz .LBB0_515
	s_add_u32 s66, s54, 0x200
	s_addc_u32 s67, s55, 0
	s_mov_b32 s2, 1
	s_branch .LBB0_508

; __device__ __forceinline__ unsigned xb_ld(unsigned* p)              { return __hip_atomic_load(p, __ATOMIC_RELAXED, __HIP_MEMORY_SCOPE_AGENT); }
; __device__ __forceinline__ unsigned xb_add(unsigned* p, unsigned v) { return __hip_atomic_fetch_add(p, v, __ATOMIC_RELAXED, __HIP_MEMORY_SCOPE_AGENT); }
; #define XB_SPIN(cond, bar) do { unsigned _sp = 0; while (cond) { __builtin_amdgcn_s_sleep(1); \
;     if ((++_sp & 255u) == 0u) { if (xb_ld(&(bar)[XB_TMO])) break; if (_sp > XB_SPIN_CAP) { atomicAdd(&(bar)[XB_TMO], 1u); break; } } } } while (0)
; __device__ __forceinline__ void xcd_barrier(const XcdBarrier& b) {
;     ...
;         const unsigned old = xb_add(&bar[XB_XSUB(b.x)], 1u);
;         const unsigned gen = old / nloc;
;         if (old + 1u == (gen + 1u) * nloc) {
;             __builtin_amdgcn_fence(__ATOMIC_RELEASE, "agent");
;             asm volatile("s_waitcnt vmcnt(0)" ::: "memory");
;             const unsigned og = xb_add(&bar[XB_TOP], 1u);
;             const unsigned tg = og / nx;
;             if (og + 1u == (tg + 1u) * nx) xb_add(&bar[XB_TOPGEN], 1u);
;             else XB_SPIN(xb_ld(&bar[XB_TOPGEN]) == tg, bar);
;             __builtin_amdgcn_fence(__ATOMIC_ACQUIRE, "agent");
;             xb_add(&bar[XB_XGEN(b.x)], 1u);
;             asm volatile("s_waitcnt vmcnt(0)" ::: "memory");
.LBB0_553:
	s_andn2_saveexec_b64 s[2:3], s[64:65]
	s_cbranch_execz .LBB0_569
	s_waitcnt lgkmcnt(0)
	v_cmp_eq_u32_e32 vcc, 1, v0
	s_cbranch_vccnz .Lwbskip_6
	buffer_wbl2 sc1
.Lwbskip_6:
	s_waitcnt vmcnt(0)
	v_mov_b32_e32 v1, 0x3000
	v_mov_b32_e32 v2, 1
	global_atomic_add v1, v1, v2, s[54:55] offset:1024 sc0
	v_cvt_f32_u32_e32 v2, v0
	v_sub_u32_e32 v3, 0, v0
	s_add_u32 s64, s54, 0x3500
	s_addc_u32 s65, s55, 0
	v_rcp_iflag_f32_e32 v2, v2
	s_mov_b64 s[68:69], -1
	v_mul_f32_e32 v2, 0x4f7ffffe, v2
	v_cvt_u32_f32_e32 v2, v2
	v_mul_lo_u32 v3, v3, v2
	v_mul_hi_u32 v3, v2, v3
	v_add_u32_e32 v2, v2, v3
	s_waitcnt vmcnt(0)
	v_mul_hi_u32 v2, v1, v2
	v_mul_lo_u32 v4, v2, v0
	v_add_u32_e32 v3, 1, v1
	v_sub_u32_e32 v1, v1, v4
	v_add_u32_e32 v5, 1, v2
	v_cmp_ge_u32_e32 vcc, v1, v0
	v_sub_u32_e32 v4, v1, v0
	s_nop 0
	v_cndmask_b32_e32 v2, v2, v5, vcc
	v_cndmask_b32_e32 v1, v1, v4, vcc
	v_add_u32_e32 v4, 1, v2
	v_cmp_ge_u32_e32 vcc, v1, v0
	s_nop 1
	v_cndmask_b32_e32 v2, v2, v4, vcc
	v_mul_lo_u32 v1, v0, v2
	v_add_u32_e32 v0, v1, v0
	v_cmp_ne_u32_e32 vcc, v3, v0
	v_mov_b64_e32 v[0:1], s[64:65]
	s_and_saveexec_b64 s[66:67], vcc
	s_cbranch_execz .LBB0_566
	v_mov_b32_e32 v0, 0
	global_load_dword v1, v0, s[64:65] sc1
	s_mov_b64 s[72:73], 0
	s_waitcnt vmcnt(0)
	v_cmp_eq_u32_e32 vcc, v1, v2
	s_and_saveexec_b64 s[70:71], vcc
	s_cbranch_execz .LBB0_565
	s_add_u32 s68, s54, 0x200
	s_addc_u32 s69, s55, 0
	s_mov_b32 s2, 1
	s_branch .LBB0_558

; __device__ __forceinline__ unsigned xb_ld(unsigned* p)              { return __hip_atomic_load(p, __ATOMIC_RELAXED, __HIP_MEMORY_SCOPE_AGENT); }
; __device__ __forceinline__ unsigned xb_add(unsigned* p, unsigned v) { return __hip_atomic_fetch_add(p, v, __ATOMIC_RELAXED, __HIP_MEMORY_SCOPE_AGENT); }
; #define XB_SPIN(cond, bar) do { unsigned _sp = 0; while (cond) { __builtin_amdgcn_s_sleep(1); \
;     if ((++_sp & 255u) == 0u) { if (xb_ld(&(bar)[XB_TMO])) break; if (_sp > XB_SPIN_CAP) { atomicAdd(&(bar)[XB_TMO], 1u); break; } } } } while (0)
; __device__ __forceinline__ void xcd_barrier(const XcdBarrier& b) {
;     ...
;         const unsigned old = xb_add(&bar[XB_XSUB(b.x)], 1u);
;         const unsigned gen = old / nloc;
;         if (old + 1u == (gen + 1u) * nloc) {
;             __builtin_amdgcn_fence(__ATOMIC_RELEASE, "agent");
;             asm volatile("s_waitcnt vmcnt(0)" ::: "memory");
;             const unsigned og = xb_add(&bar[XB_TOP], 1u);
;             const unsigned tg = og / nx;
;             if (og + 1u == (tg + 1u) * nx) xb_add(&bar[XB_TOPGEN], 1u);
;             else XB_SPIN(xb_ld(&bar[XB_TOPGEN]) == tg, bar);
;             __builtin_amdgcn_fence(__ATOMIC_ACQUIRE, "agent");
;             xb_add(&bar[XB_XGEN(b.x)], 1u);
;             asm volatile("s_waitcnt vmcnt(0)" ::: "memory");
.LBB0_1085:
	s_andn2_saveexec_b64 s[2:3], s[12:13]
	s_cbranch_execz .LBB0_1101
	s_waitcnt lgkmcnt(0)
	v_cmp_eq_u32_e32 vcc, 1, v0
	s_cbranch_vccnz .Lwbskip_13
	buffer_wbl2 sc1
.Lwbskip_13:
	s_waitcnt vmcnt(0)
	v_mov_b32_e32 v1, 0x3000
	v_mov_b32_e32 v2, 1
	global_atomic_add v1, v1, v2, s[54:55] offset:1024 sc0
	v_cvt_f32_u32_e32 v2, v0
	v_sub_u32_e32 v3, 0, v0
	s_add_u32 s12, s54, 0x3500
	s_addc_u32 s13, s55, 0
	v_rcp_iflag_f32_e32 v2, v2
	s_mov_b64 s[16:17], -1
	v_mul_f32_e32 v2, 0x4f7ffffe, v2
	v_cvt_u32_f32_e32 v2, v2
	v_mul_lo_u32 v3, v3, v2
	v_mul_hi_u32 v3, v2, v3
	v_add_u32_e32 v2, v2, v3
	s_waitcnt vmcnt(0)
	v_mul_hi_u32 v2, v1, v2
	v_mul_lo_u32 v4, v2, v0
	v_add_u32_e32 v3, 1, v1
	v_sub_u32_e32 v1, v1, v4
	v_add_u32_e32 v5, 1, v2
	v_cmp_ge_u32_e32 vcc, v1, v0
	v_sub_u32_e32 v4, v1, v0
	s_nop 0
	v_cndmask_b32_e32 v2, v2, v5, vcc
	v_cndmask_b32_e32 v1, v1, v4, vcc
	v_add_u32_e32 v4, 1, v2
	v_cmp_ge_u32_e32 vcc, v1, v0
	s_nop 1
	v_cndmask_b32_e32 v2, v2, v4, vcc
	v_mul_lo_u32 v1, v0, v2
	v_add_u32_e32 v0, v1, v0
	v_cmp_ne_u32_e32 vcc, v3, v0
	v_mov_b64_e32 v[0:1], s[12:13]
	s_and_saveexec_b64 s[14:15], vcc
	s_cbranch_execz .LBB0_1098
	v_mov_b32_e32 v0, 0
	global_load_dword v1, v0, s[12:13] sc1
	s_mov_b64 s[48:49], 0
	s_waitcnt vmcnt(0)
	v_cmp_eq_u32_e32 vcc, v1, v2
	s_and_saveexec_b64 s[46:47], vcc
	s_cbranch_execz .LBB0_1097
	s_add_u32 s16, s54, 0x200
	s_addc_u32 s17, s55, 0
	s_mov_b32 s2, 1
	s_branch .LBB0_1090

; __device__ __forceinline__ unsigned xb_ld(unsigned* p)              { return __hip_atomic_load(p, __ATOMIC_RELAXED, __HIP_MEMORY_SCOPE_AGENT); }
; __device__ __forceinline__ unsigned xb_add(unsigned* p, unsigned v) { return __hip_atomic_fetch_add(p, v, __ATOMIC_RELAXED, __HIP_MEMORY_SCOPE_AGENT); }
; #define XB_SPIN(cond, bar) do { unsigned _sp = 0; while (cond) { __builtin_amdgcn_s_sleep(1); \
;     if ((++_sp & 255u) == 0u) { if (xb_ld(&(bar)[XB_TMO])) break; if (_sp > XB_SPIN_CAP) { atomicAdd(&(bar)[XB_TMO], 1u); break; } } } } while (0)
; __device__ __forceinline__ void xcd_barrier(const XcdBarrier& b) {
;     ...
;         const unsigned old = xb_add(&bar[XB_XSUB(b.x)], 1u);
;         const unsigned gen = old / nloc;
;         if (old + 1u == (gen + 1u) * nloc) {
;             __builtin_amdgcn_fence(__ATOMIC_RELEASE, "agent");
;             asm volatile("s_waitcnt vmcnt(0)" ::: "memory");
;             const unsigned og = xb_add(&bar[XB_TOP], 1u);
;             const unsigned tg = og / nx;
;             if (og + 1u == (tg + 1u) * nx) xb_add(&bar[XB_TOPGEN], 1u);
;             else XB_SPIN(xb_ld(&bar[XB_TOPGEN]) == tg, bar);
;             __builtin_amdgcn_fence(__ATOMIC_ACQUIRE, "agent");
;             xb_add(&bar[XB_XGEN(b.x)], 1u);
;             asm volatile("s_waitcnt vmcnt(0)" ::: "memory");
.LBB0_1136:
	s_andn2_saveexec_b64 s[6:7], s[6:7]
	s_cbranch_execz .LBB0_1152
	s_waitcnt lgkmcnt(0)
	v_cmp_eq_u32_e32 vcc, 1, v0
	s_cbranch_vccnz .Lwbskip_14
	buffer_wbl2 sc1
.Lwbskip_14:
	s_waitcnt vmcnt(0)
	v_mov_b32_e32 v1, 0x3000
	v_mov_b32_e32 v2, 1
	global_atomic_add v1, v1, v2, s[54:55] offset:1024 sc0
	v_cvt_f32_u32_e32 v2, v0
	v_sub_u32_e32 v3, 0, v0
	s_add_u32 s6, s54, 0x3500
	s_addc_u32 s7, s55, 0
	v_rcp_iflag_f32_e32 v2, v2
	s_mov_b64 s[14:15], -1
	v_mul_f32_e32 v2, 0x4f7ffffe, v2
	v_cvt_u32_f32_e32 v2, v2
	v_mul_lo_u32 v3, v3, v2
	v_mul_hi_u32 v3, v2, v3
	v_add_u32_e32 v2, v2, v3
	s_waitcnt vmcnt(0)
	v_mul_hi_u32 v2, v1, v2
	v_mul_lo_u32 v4, v2, v0
	v_add_u32_e32 v3, 1, v1
	v_sub_u32_e32 v1, v1, v4
	v_add_u32_e32 v5, 1, v2
	v_cmp_ge_u32_e32 vcc, v1, v0
	v_sub_u32_e32 v4, v1, v0
	s_nop 0
	v_cndmask_b32_e32 v2, v2, v5, vcc
	v_cndmask_b32_e32 v1, v1, v4, vcc
	v_add_u32_e32 v4, 1, v2
	v_cmp_ge_u32_e32 vcc, v1, v0
	s_nop 1
	v_cndmask_b32_e32 v2, v2, v4, vcc
	v_mul_lo_u32 v1, v0, v2
	v_add_u32_e32 v0, v1, v0
	v_cmp_ne_u32_e32 vcc, v3, v0
	v_mov_b64_e32 v[0:1], s[6:7]
	s_and_saveexec_b64 s[12:13], vcc
	s_cbranch_execz .LBB0_1149
	v_mov_b32_e32 v0, 0
	global_load_dword v1, v0, s[6:7] sc1
	s_mov_b64 s[42:43], 0
	s_waitcnt vmcnt(0)
	v_cmp_eq_u32_e32 vcc, v1, v2
	s_and_saveexec_b64 s[16:17], vcc
	s_cbranch_execz .LBB0_1148
	s_add_u32 s14, s54, 0x200
	s_addc_u32 s15, s55, 0
	s_mov_b32 s11, 1
	s_branch .LBB0_1141

; __device__ __forceinline__ unsigned xb_ld(unsigned* p)              { return __hip_atomic_load(p, __ATOMIC_RELAXED, __HIP_MEMORY_SCOPE_AGENT); }
; __device__ __forceinline__ unsigned xb_add(unsigned* p, unsigned v) { return __hip_atomic_fetch_add(p, v, __ATOMIC_RELAXED, __HIP_MEMORY_SCOPE_AGENT); }
; #define XB_SPIN(cond, bar) do { unsigned _sp = 0; while (cond) { __builtin_amdgcn_s_sleep(1); \
;     if ((++_sp & 255u) == 0u) { if (xb_ld(&(bar)[XB_TMO])) break; if (_sp > XB_SPIN_CAP) { atomicAdd(&(bar)[XB_TMO], 1u); break; } } } } while (0)
; __device__ __forceinline__ void xcd_barrier(const XcdBarrier& b) {
;     ...
;             __builtin_amdgcn_fence(__ATOMIC_RELEASE, "agent");
;             asm volatile("s_waitcnt vmcnt(0)" ::: "memory");
;             const unsigned og = xb_add(&bar[XB_TOP], 1u);
;             const unsigned tg = og / nx;
;             if (og + 1u == (tg + 1u) * nx) xb_add(&bar[XB_TOPGEN], 1u);
;             else XB_SPIN(xb_ld(&bar[XB_TOPGEN]) == tg, bar);
.Lwbskip_15:
	s_waitcnt vmcnt(0)
	v_mov_b32_e32 v1, 0x3000
	v_mov_b32_e32 v2, 1
	global_atomic_add v1, v1, v2, s[54:55] offset:1024 sc0
	v_cvt_f32_u32_e32 v2, v0
	v_sub_u32_e32 v3, 0, v0
	s_add_u32 s6, s54, 0x3500
	s_addc_u32 s7, s55, 0
	v_rcp_iflag_f32_e32 v2, v2
	s_mov_b64 s[14:15], -1
	v_mul_f32_e32 v2, 0x4f7ffffe, v2
	v_cvt_u32_f32_e32 v2, v2
	v_mul_lo_u32 v3, v3, v2
	v_mul_hi_u32 v3, v2, v3
	v_add_u32_e32 v2, v2, v3
	s_waitcnt vmcnt(0)
	v_mul_hi_u32 v2, v1, v2
	v_mul_lo_u32 v4, v2, v0
	v_add_u32_e32 v3, 1, v1
	v_sub_u32_e32 v1, v1, v4
	v_add_u32_e32 v5, 1, v2
	v_cmp_ge_u32_e32 vcc, v1, v0
	v_sub_u32_e32 v4, v1, v0
	s_nop 0
	v_cndmask_b32_e32 v2, v2, v5, vcc
	v_cndmask_b32_e32 v1, v1, v4, vcc
	v_add_u32_e32 v4, 1, v2
	v_cmp_ge_u32_e32 vcc, v1, v0
	s_nop 1
	v_cndmask_b32_e32 v2, v2, v4, vcc
	v_mul_lo_u32 v1, v0, v2
	v_add_u32_e32 v0, v1, v0
	v_cmp_ne_u32_e32 vcc, v3, v0
	v_mov_b64_e32 v[0:1], s[6:7]
	s_and_saveexec_b64 s[12:13], vcc
	s_cbranch_execz .LBB0_1199
	v_mov_b32_e32 v0, 0
	global_load_dword v1, v0, s[6:7] sc1
	s_mov_b64 s[18:19], 0
	s_waitcnt vmcnt(0)
	v_cmp_eq_u32_e32 vcc, v1, v2
	s_and_saveexec_b64 s[16:17], vcc
	s_cbranch_execz .LBB0_1198
	s_add_u32 s14, s54, 0x200
	s_addc_u32 s15, s55, 0
	s_mov_b32 s11, 1
	s_branch .LBB0_1191

; __device__ __forceinline__ unsigned xb_ld(unsigned* p)              { return __hip_atomic_load(p, __ATOMIC_RELAXED, __HIP_MEMORY_SCOPE_AGENT); }
; __device__ __forceinline__ unsigned xb_add(unsigned* p, unsigned v) { return __hip_atomic_fetch_add(p, v, __ATOMIC_RELAXED, __HIP_MEMORY_SCOPE_AGENT); }
; #define XB_SPIN(cond, bar) do { unsigned _sp = 0; while (cond) { __builtin_amdgcn_s_sleep(1); \
;     if ((++_sp & 255u) == 0u) { if (xb_ld(&(bar)[XB_TMO])) break; if (_sp > XB_SPIN_CAP) { atomicAdd(&(bar)[XB_TMO], 1u); break; } } } } while (0)
; __device__ __forceinline__ void xcd_barrier(const XcdBarrier& b) {
;     ...
;             __builtin_amdgcn_fence(__ATOMIC_RELEASE, "agent");
;             asm volatile("s_waitcnt vmcnt(0)" ::: "memory");
;             const unsigned og = xb_add(&bar[XB_TOP], 1u);
;             const unsigned tg = og / nx;
;             if (og + 1u == (tg + 1u) * nx) xb_add(&bar[XB_TOPGEN], 1u);
;             else XB_SPIN(xb_ld(&bar[XB_TOPGEN]) == tg, bar);
.Lwbskip_18:
	s_waitcnt vmcnt(0)
	v_mov_b32_e32 v1, 0x3000
	v_mov_b32_e32 v2, 1
	global_atomic_add v1, v1, v2, s[54:55] offset:1024 sc0
	v_cvt_f32_u32_e32 v2, v0
	v_sub_u32_e32 v3, 0, v0
	s_add_u32 s6, s54, 0x3500
	s_addc_u32 s7, s55, 0
	v_rcp_iflag_f32_e32 v2, v2
	s_mov_b64 s[10:11], -1
	v_mul_f32_e32 v2, 0x4f7ffffe, v2
	v_cvt_u32_f32_e32 v2, v2
	v_mul_lo_u32 v3, v3, v2
	v_mul_hi_u32 v3, v2, v3
	v_add_u32_e32 v2, v2, v3
	s_waitcnt vmcnt(0)
	v_mul_hi_u32 v2, v1, v2
	v_mul_lo_u32 v4, v2, v0
	v_add_u32_e32 v3, 1, v1
	v_sub_u32_e32 v1, v1, v4
	v_add_u32_e32 v5, 1, v2
	v_cmp_ge_u32_e32 vcc, v1, v0
	v_sub_u32_e32 v4, v1, v0
	s_nop 0
	v_cndmask_b32_e32 v2, v2, v5, vcc
	v_cndmask_b32_e32 v1, v1, v4, vcc
	v_add_u32_e32 v4, 1, v2
	v_cmp_ge_u32_e32 vcc, v1, v0
	s_nop 1
	v_cndmask_b32_e32 v2, v2, v4, vcc
	v_mul_lo_u32 v1, v0, v2
	v_add_u32_e32 v0, v1, v0
	v_cmp_ne_u32_e32 vcc, v3, v0
	v_mov_b64_e32 v[0:1], s[6:7]
	s_and_saveexec_b64 s[8:9], vcc
	s_cbranch_execz .LBB0_1427
	v_mov_b32_e32 v0, 0
	global_load_dword v1, v0, s[6:7] sc1
	s_mov_b64 s[14:15], 0
	s_waitcnt vmcnt(0)
	v_cmp_eq_u32_e32 vcc, v1, v2
	s_and_saveexec_b64 s[12:13], vcc
	s_cbranch_execz .LBB0_1426
	s_add_u32 s10, s54, 0x200
	s_addc_u32 s11, s55, 0
	s_mov_b32 s20, 1
	s_branch .LBB0_1419
